# v031 + SSD per-token exp LDS table, causal mask via scalar lane-mask constants, E2 operand folding (fewer VALU ops in the VALU-bound P3)
# speedup vs baseline: 1.0113x; 1.0054x over previous
.LBB0_572:
	v_mov_b32_e32 v152, v182
	s_nop 0
	v_readlane_b32 s32, v165, 31
	s_nop 3
	v_sub_f32_e32 v248, s32, v165
	v_exp_f32_e32 v249, v165
	v_exp_f32_e32 v248, v248
	v_cmp_gt_u32_e32 vcc, 32, v152
	s_and_saveexec_b64 s[6:7], vcc
	v_lshl_add_u32 v64, v152, 3, s49
	ds_write_b64 v64, v[164:165]
	v_lshl_add_u32 v250, v152, 2, s49
	ds_write_b32 v250, v248 offset:1024
	ds_write_b32 v250, v249 offset:1152
	s_or_b64 exec, exec, s[6:7]
	s_bitcmp1_b32 s34, 0
	s_cselect_b32 s6, 0xe000, 0
	s_add_i32 s42, s6, 0
	v_and_b32_e32 v197, 31, v152
	v_ashrrev_i32_e32 v196, 5, v152
	s_add_i32 s34, s42, s39
	s_waitcnt lgkmcnt(0)
	v_lshlrev_b32_e32 v65, 8, v196
	v_lshlrev_b32_e32 v66, 1, v197
	v_and_b32_e32 v164, 0xffffffe0, v152
	s_waitcnt lgkmcnt(0)
	v_add3_u32 v195, s34, v65, v66
	v_add_u32_e32 v90, s49, v164
	v_mov_b32_e32 v64, s49
	ds_read_b128 v[124:127], v90
	ds_read_b128 v[120:123], v90 offset:16
	ds_read_b32 v198, v64 offset:252
	ds_read_u16 v66, v195 offset:32768
	ds_read_u16 v67, v195 offset:32832
	ds_read_u16 v70, v195 offset:32896
	ds_read_u16 v71, v195 offset:32960
	ds_read_u16 v74, v195 offset:33280
	ds_read_u16 v75, v195 offset:33344
	ds_read_u16 v78, v195 offset:33408
	ds_read_u16 v94, v195 offset:34496
	ds_read_b128 v[132:135], v90 offset:64
	ds_read_b128 v[128:131], v90 offset:80
	ds_read_b128 v[112:115], v90 offset:128
	ds_read_u16 v79, v195 offset:33472
	ds_read_u16 v82, v195 offset:33792
	ds_read_u16 v83, v195 offset:33856
	ds_read_u16 v86, v195 offset:33920
	ds_read_u16 v87, v195 offset:33984
	ds_read_u16 v91, v195 offset:34304
	ds_read_u16 v92, v195 offset:34368
	ds_read_u16 v95, v195 offset:34432
	ds_read_b128 v[116:119], v90 offset:144
	ds_read_b128 v[104:107], v90 offset:192
	ds_read_b128 v[100:103], v90 offset:208
	v_lshrrev_b32_e32 v250, 1, v164
	v_add_u32_e32 v250, s49, v250
	ds_read_b128 v[216:219], v250 offset:1024
	ds_read_b128 v[220:223], v250 offset:1056
	ds_read_b128 v[224:227], v250 offset:1088
	ds_read_b128 v[228:231], v250 offset:1120
	ds_read_b128 v[232:235], v250 offset:1152
	ds_read_b128 v[236:239], v250 offset:1184
	ds_read_b128 v[240:243], v250 offset:1216
	ds_read_b128 v[244:247], v250 offset:1248
	s_waitcnt lgkmcnt(0)
	v_lshlrev_b32_e32 v169, 16, v92
	v_lshlrev_b32_e32 v181, 16, v67
	v_lshlrev_b32_e32 v180, 16, v66
	v_mov_b32_e32 v66, v124
	v_mov_b32_e32 v67, v126
	v_lshlrev_b32_e32 v179, 16, v71
	v_lshlrev_b32_e32 v178, 16, v70
	v_mov_b32_e32 v70, v120
	v_mov_b32_e32 v71, v122
	v_lshlrev_b32_e32 v177, 16, v75
	v_lshlrev_b32_e32 v176, 16, v74
	v_mov_b32_e32 v74, v132
	v_mov_b32_e32 v75, v134
	v_lshlrev_b32_e32 v175, 16, v79
	v_lshlrev_b32_e32 v174, 16, v78
	v_mov_b32_e32 v78, v128
	v_mov_b32_e32 v79, v130
	v_lshlrev_b32_e32 v173, 16, v83
	v_lshlrev_b32_e32 v172, 16, v82
	v_mov_b32_e32 v82, v112
	v_mov_b32_e32 v83, v114
	v_lshlrev_b32_e32 v171, 16, v87
	v_lshlrev_b32_e32 v170, 16, v86
	v_mov_b32_e32 v86, v116
	v_mov_b32_e32 v87, v118
	v_lshlrev_b32_e32 v168, 16, v91
	v_mov_b32_e32 v90, v104
	v_mov_b32_e32 v91, v106
	v_lshlrev_b32_e32 v167, 16, v94
	v_lshlrev_b32_e32 v166, 16, v95
	v_mov_b32_e32 v94, v100
	v_mov_b32_e32 v95, v102
	v_pk_mul_f32 v[66:67], v[66:67], v[180:181]
	v_pk_mul_f32 v[70:71], v[70:71], v[178:179]
	v_pk_mul_f32 v[74:75], v[74:75], v[176:177]
	v_pk_mul_f32 v[78:79], v[78:79], v[174:175]
	v_pk_mul_f32 v[82:83], v[82:83], v[172:173]
	v_pk_mul_f32 v[86:87], v[86:87], v[170:171]
	v_pk_mul_f32 v[90:91], v[90:91], v[168:169]
	v_pk_mul_f32 v[94:95], v[94:95], v[166:167]
	v_pk_mul_f32 v[64:65], v[66:67], v[216:217]
	v_pk_mul_f32 v[68:69], v[70:71], v[218:219]
	v_pk_mul_f32 v[72:73], v[74:75], v[220:221]
	v_pk_mul_f32 v[76:77], v[78:79], v[222:223]
	v_pk_mul_f32 v[80:81], v[82:83], v[224:225]
	v_pk_mul_f32 v[84:85], v[86:87], v[226:227]
	v_pk_mul_f32 v[88:89], v[90:91], v[228:229]
	v_pk_mul_f32 v[92:93], v[94:95], v[230:231]
	v_cvt_pk_bf16_f32 v148, v66, v67
	v_cvt_pk_bf16_f32 v149, v70, v71
	v_cvt_pk_bf16_f32 v150, v74, v75
	v_cvt_pk_bf16_f32 v151, v78, v79
	v_cvt_pk_bf16_f32 v108, v64, v65
	v_cvt_pk_bf16_f32 v109, v68, v69
	v_cvt_pk_bf16_f32 v110, v72, v73
	v_cvt_pk_bf16_f32 v111, v76, v77
	v_cvt_pk_bf16_f32 v140, v82, v83
	v_cvt_pk_bf16_f32 v141, v86, v87
	v_cvt_pk_bf16_f32 v142, v90, v91
	v_cvt_pk_bf16_f32 v143, v94, v95
	v_cvt_pk_bf16_f32 v96, v80, v81
	v_cvt_pk_bf16_f32 v97, v84, v85
	v_cvt_pk_bf16_f32 v98, v88, v89
	v_cvt_pk_bf16_f32 v99, v92, v93
	s_setprio 1
	v_bitop3_b32 v64, v196, v152, 15 bitop3:0x78
	v_lshlrev_b32_e32 v100, 8, v197
	v_lshlrev_b32_e32 v64, 4, v64
	v_add3_u32 v68, v64, v100, s42
	ds_read_b128 v[80:83], v68 offset:8192
	ds_read_b128 v[84:87], v68
	v_cvt_pk_bf16_f32 v64, v0, v1
	v_cvt_pk_bf16_f32 v65, v2, v3
	v_cvt_pk_bf16_f32 v66, v4, v5
	v_cvt_pk_bf16_f32 v67, v6, v7
	v_add_u32_e32 v104, 2, v196
	v_bitop3_b32 v102, v104, v152, 15 bitop3:0x78
	s_waitcnt lgkmcnt(0)
	v_mfma_f32_32x32x16_bf16 v[64:79], v[80:83], v[64:67], 0
	v_lshlrev_b32_e32 v102, 4, v102
	v_add3_u32 v102, v102, v100, s42
	ds_read_b128 v[136:139], v102 offset:8192
	ds_read_b128 v[144:147], v102
	v_add_u32_e32 v102, 4, v196
	v_bitop3_b32 v102, v102, v152, 15 bitop3:0x78
	v_lshlrev_b32_e32 v102, 4, v102
	v_cvt_pk_bf16_f32 v200, v8, v9
	v_mfma_f32_32x32x16_bf16 v[80:95], v[84:87], v[80:83], 0
	v_cvt_pk_bf16_f32 v201, v10, v11
	v_cvt_pk_bf16_f32 v202, v12, v13
	v_cvt_pk_bf16_f32 v203, v14, v15
	v_add3_u32 v102, v102, v100, s42
	v_cvt_pk_bf16_f32 v208, v48, v49
	v_cvt_pk_bf16_f32 v209, v50, v51
	v_cvt_pk_bf16_f32 v210, v52, v53
	s_waitcnt lgkmcnt(0)
	v_mfma_f32_32x32x16_bf16 v[80:95], v[144:147], v[136:139], v[80:95]
	v_cvt_pk_bf16_f32 v211, v54, v55
	v_mfma_f32_32x32x16_bf16 v[64:79], v[136:139], v[200:203], v[64:79]
	ds_read_b128 v[136:139], v102 offset:8192
	ds_read_b128 v[144:147], v102
	v_add_u32_e32 v102, 6, v196
	v_bitop3_b32 v102, v102, v152, 15 bitop3:0x78
	v_lshlrev_b32_e32 v102, 4, v102
	v_cvt_pk_bf16_f32 v200, v16, v17
	v_cvt_pk_bf16_f32 v201, v18, v19
	v_cvt_pk_bf16_f32 v202, v20, v21
	s_waitcnt lgkmcnt(0)
	v_mfma_f32_32x32x16_bf16 v[80:95], v[144:147], v[136:139], v[80:95]
	v_cvt_pk_bf16_f32 v203, v22, v23
	v_add3_u32 v102, v102, v100, s42
	s_nop 0
	v_mfma_f32_32x32x16_bf16 v[64:79], v[136:139], v[200:203], v[64:79]
	ds_read_b128 v[136:139], v102 offset:8192
	ds_read_b128 v[144:147], v102
	v_add_u32_e32 v102, 8, v196
	v_bitop3_b32 v102, v102, v152, 15 bitop3:0x78
	v_lshlrev_b32_e32 v102, 4, v102
	v_cvt_pk_bf16_f32 v200, v24, v25
	v_cvt_pk_bf16_f32 v201, v26, v27
	v_cvt_pk_bf16_f32 v202, v28, v29
	s_waitcnt lgkmcnt(0)
	v_mfma_f32_32x32x16_bf16 v[80:95], v[144:147], v[136:139], v[80:95]
	v_cvt_pk_bf16_f32 v203, v30, v31
	v_add3_u32 v102, v102, v100, s42
	s_nop 0
	v_mfma_f32_32x32x16_bf16 v[64:79], v[136:139], v[200:203], v[64:79]
	ds_read_b128 v[136:139], v102 offset:8192
	ds_read_b128 v[144:147], v102
	v_add_u32_e32 v102, 10, v196
	v_bitop3_b32 v102, v102, v152, 15 bitop3:0x78
	v_lshlrev_b32_e32 v102, 4, v102
	v_cvt_pk_bf16_f32 v200, v32, v33
	v_cvt_pk_bf16_f32 v201, v34, v35
	v_cvt_pk_bf16_f32 v202, v36, v37
	s_waitcnt lgkmcnt(0)
	v_mfma_f32_32x32x16_bf16 v[80:95], v[144:147], v[136:139], v[80:95]
	v_cvt_pk_bf16_f32 v203, v38, v39
	v_add3_u32 v102, v102, v100, s42
	s_nop 0
	v_mfma_f32_32x32x16_bf16 v[64:79], v[136:139], v[200:203], v[64:79]
	ds_read_b128 v[136:139], v102 offset:8192
	ds_read_b128 v[144:147], v102
	v_add_u32_e32 v102, 12, v196
	v_bitop3_b32 v102, v102, v152, 15 bitop3:0x78
	v_lshlrev_b32_e32 v102, 4, v102
	v_cvt_pk_bf16_f32 v200, v40, v41
	v_cvt_pk_bf16_f32 v201, v42, v43
	v_cvt_pk_bf16_f32 v202, v44, v45
	s_waitcnt lgkmcnt(0)
	v_mfma_f32_32x32x16_bf16 v[80:95], v[144:147], v[136:139], v[80:95]
	v_cvt_pk_bf16_f32 v203, v46, v47
	v_add3_u32 v102, v102, v100, s42
	v_cvt_pk_bf16_f32 v144, v56, v57
	v_cvt_pk_bf16_f32 v145, v58, v59
	v_cvt_pk_bf16_f32 v146, v60, v61
	v_cvt_pk_bf16_f32 v147, v62, v63
	v_mfma_f32_32x32x16_bf16 v[64:79], v[136:139], v[200:203], v[64:79]
	ds_read_b128 v[200:203], v102 offset:8192
	ds_read_b128 v[204:207], v102
	v_add_u32_e32 v102, 14, v196
	v_bitop3_b32 v102, v102, v152, 15 bitop3:0x78
	v_lshlrev_b32_e32 v102, 4, v102
	v_add3_u32 v100, v102, v100, s42
	ds_read_b128 v[136:139], v100 offset:8192
	ds_read_b128 v[212:215], v100
	s_waitcnt lgkmcnt(0)
	v_mfma_f32_32x32x16_bf16 v[80:95], v[204:207], v[200:203], v[80:95]
	v_mfma_f32_32x32x16_bf16 v[80:95], v[212:215], v[136:139], v[80:95]
	s_setprio 0
	v_mfma_f32_32x32x16_bf16 v[64:79], v[200:203], v[208:211], v[64:79]
	v_mfma_f32_32x32x16_bf16 v[64:79], v[136:139], v[144:147], v[64:79]
	v_sub_f32_e32 v216, v165, v125
	v_sub_f32_e32 v217, v165, v127
	v_sub_f32_e32 v218, v165, v121
	v_sub_f32_e32 v219, v165, v123
	v_sub_f32_e32 v220, v165, v133
	v_sub_f32_e32 v221, v165, v135
	v_sub_f32_e32 v222, v165, v129
	v_sub_f32_e32 v223, v165, v131
	v_sub_f32_e32 v224, v165, v113
	v_sub_f32_e32 v225, v165, v115
	v_sub_f32_e32 v226, v165, v117
	v_sub_f32_e32 v227, v165, v119
	v_sub_f32_e32 v228, v165, v105
	v_sub_f32_e32 v229, v165, v107
	v_sub_f32_e32 v230, v165, v101
	v_sub_f32_e32 v231, v165, v103
	v_exp_f32_e32 v216, v216
	v_exp_f32_e32 v217, v217
	v_exp_f32_e32 v218, v218
	v_exp_f32_e32 v219, v219
	v_exp_f32_e32 v220, v220
	v_exp_f32_e32 v221, v221
	v_exp_f32_e32 v222, v222
	v_exp_f32_e32 v223, v223
	v_exp_f32_e32 v224, v224
	v_exp_f32_e32 v225, v225
	v_exp_f32_e32 v226, v226
	v_exp_f32_e32 v227, v227
	v_exp_f32_e32 v228, v228
	v_exp_f32_e32 v229, v229
	v_exp_f32_e32 v230, v230
	v_exp_f32_e32 v231, v231
	v_mul_f32_e32 v216, v216, v80
	v_mul_f32_e32 v217, v217, v81
	v_mul_f32_e32 v218, v218, v82
	v_mul_f32_e32 v219, v219, v83
	v_mul_f32_e32 v220, v220, v84
	v_mul_f32_e32 v221, v221, v85
	v_mul_f32_e32 v222, v222, v86
	v_mul_f32_e32 v223, v223, v87
	v_mul_f32_e32 v224, v224, v88
	v_mul_f32_e32 v225, v225, v89
	v_mul_f32_e32 v226, v226, v90
	v_mul_f32_e32 v227, v227, v91
	v_mul_f32_e32 v228, v228, v92
	v_mul_f32_e32 v229, v229, v93
	v_mul_f32_e32 v230, v230, v94
	v_mul_f32_e32 v231, v231, v95
	s_mov_b32 s6, 0xffffffff
	s_mov_b32 s7, 0xfffffff0
	v_cndmask_b32_e64 v216, 0, v216, s[6:7]
	s_mov_b32 s6, 0xfffffffe
	s_mov_b32 s7, 0xffffffe0
	v_cndmask_b32_e64 v217, 0, v217, s[6:7]
	s_mov_b32 s6, 0xfffffffc
	s_mov_b32 s7, 0xffffffc0
	v_cndmask_b32_e64 v218, 0, v218, s[6:7]
	s_mov_b32 s6, 0xfffffff8
	s_mov_b32 s7, 0xffffff80
	v_cndmask_b32_e64 v219, 0, v219, s[6:7]
	s_mov_b32 s6, 0xffffff00
	s_mov_b32 s7, 0xfffff000
	v_cndmask_b32_e64 v220, 0, v220, s[6:7]
	s_mov_b32 s6, 0xfffffe00
	s_mov_b32 s7, 0xffffe000
	v_cndmask_b32_e64 v221, 0, v221, s[6:7]
	s_mov_b32 s6, 0xfffffc00
	s_mov_b32 s7, 0xffffc000
	v_cndmask_b32_e64 v222, 0, v222, s[6:7]
	s_mov_b32 s6, 0xfffff800
	s_mov_b32 s7, 0xffff8000
	v_cndmask_b32_e64 v223, 0, v223, s[6:7]
	s_mov_b32 s6, 0xffff0000
	s_mov_b32 s7, 0xfff00000
	v_cndmask_b32_e64 v224, 0, v224, s[6:7]
	s_mov_b32 s6, 0xfffe0000
	s_mov_b32 s7, 0xffe00000
	v_cndmask_b32_e64 v225, 0, v225, s[6:7]
	s_mov_b32 s6, 0xfffc0000
	s_mov_b32 s7, 0xffc00000
	v_cndmask_b32_e64 v226, 0, v226, s[6:7]
	s_mov_b32 s6, 0xfff80000
	s_mov_b32 s7, 0xff800000
	v_cndmask_b32_e64 v227, 0, v227, s[6:7]
	s_mov_b32 s6, 0xff000000
	s_mov_b32 s7, 0xf0000000
	v_cndmask_b32_e64 v228, 0, v228, s[6:7]
	s_mov_b32 s6, 0xfe000000
	s_mov_b32 s7, 0xe0000000
	v_cndmask_b32_e64 v229, 0, v229, s[6:7]
	s_mov_b32 s6, 0xfc000000
	s_mov_b32 s7, 0xc0000000
	v_cndmask_b32_e64 v230, 0, v230, s[6:7]
	s_mov_b32 s6, 0xf8000000
	s_mov_b32 s7, 0x80000000
	v_cndmask_b32_e64 v231, 0, v231, s[6:7]
	v_cvt_pk_bf16_f32 v80, v216, v217
	v_cvt_pk_bf16_f32 v81, v218, v219
	v_cvt_pk_bf16_f32 v82, v220, v221
	v_cvt_pk_bf16_f32 v83, v222, v223
	v_lshrrev_b32_e32 v112, 2, v152
	v_bitop3_b32 v114, v112, v196, 3 bitop3:0x6c
	v_mfma_f32_32x32x16_bf16 v[80:95], v[80:83], v[148:151], 0
	v_cvt_pk_bf16_f32 v148, v224, v225
	v_cvt_pk_bf16_f32 v149, v226, v227
	v_cvt_pk_bf16_f32 v150, v228, v229
	v_cvt_pk_bf16_f32 v151, v230, v231
	v_bitop3_b32 v104, v104, v112, 3 bitop3:0x78
	v_lshlrev_b32_e32 v102, 6, v197
	v_add_u32_e32 v106, s42, v102
	v_lshl_add_u32 v114, v114, 4, v106
	v_mfma_f32_32x32x16_bf16 v[80:95], v[148:151], v[140:143], v[80:95]
	ds_read_b128 v[140:143], v114 offset:16384
	ds_read_b128 v[148:151], v114 offset:18432
	v_exp_f32_e32 v100, v198
	v_lshl_add_u32 v104, v104, 4, v106
	v_pk_mul_f32 v[14:15], v[14:15], v[100:101] op_sel_hi:[1,0]
	v_pk_mul_f32 v[12:13], v[12:13], v[100:101] op_sel_hi:[1,0]
	v_pk_mul_f32 v[10:11], v[10:11], v[100:101] op_sel_hi:[1,0]
	v_pk_mul_f32 v[8:9], v[8:9], v[100:101] op_sel_hi:[1,0]
	v_pk_mul_f32 v[6:7], v[6:7], v[100:101] op_sel_hi:[1,0]
	v_pk_mul_f32 v[4:5], v[4:5], v[100:101] op_sel_hi:[1,0]
	v_pk_mul_f32 v[2:3], v[2:3], v[100:101] op_sel_hi:[1,0]
	v_pk_mul_f32 v[0:1], v[0:1], v[100:101] op_sel_hi:[1,0]
	v_pk_mul_f32 v[30:31], v[30:31], v[100:101] op_sel_hi:[1,0]
	v_pk_mul_f32 v[28:29], v[28:29], v[100:101] op_sel_hi:[1,0]
	s_waitcnt lgkmcnt(0)
	v_mfma_f32_32x32x16_bf16 v[0:15], v[140:143], v[108:111], v[0:15]
	ds_read_b128 v[140:143], v104 offset:16384
	ds_read_b128 v[196:199], v104 offset:18432
	v_mul_f32_e64 v26, v26, v100
	v_mul_f32_e64 v27, v27, v100
	v_mul_f32_e64 v24, v24, v100
	v_mul_f32_e64 v25, v25, v100
	v_pk_mul_f32 v[22:23], v[22:23], v[100:101] op_sel_hi:[1,0]
	v_pk_mul_f32 v[20:21], v[20:21], v[100:101] op_sel_hi:[1,0]
	v_pk_mul_f32 v[18:19], v[18:19], v[100:101] op_sel_hi:[1,0]
	v_pk_mul_f32 v[16:17], v[16:17], v[100:101] op_sel_hi:[1,0]
	s_waitcnt lgkmcnt(0)
	v_mfma_f32_32x32x16_bf16 v[0:15], v[140:143], v[96:99], v[0:15]
	ds_read_b128 v[140:143], v114 offset:20480
	v_mul_f32_e64 v46, v46, v100
	v_mul_f32_e64 v47, v47, v100
	v_mul_f32_e64 v44, v44, v100
	v_mul_f32_e64 v45, v45, v100
	v_pk_mul_f32 v[42:43], v[42:43], v[100:101] op_sel_hi:[1,0]
	v_pk_mul_f32 v[40:41], v[40:41], v[100:101] op_sel_hi:[1,0]
	v_pk_mul_f32 v[38:39], v[38:39], v[100:101] op_sel_hi:[1,0]
	v_pk_mul_f32 v[36:37], v[36:37], v[100:101] op_sel_hi:[1,0]
	v_mfma_f32_32x32x16_bf16 v[16:31], v[148:151], v[108:111], v[16:31]
	v_mul_f32_e64 v34, v34, v100
	v_mul_f32_e64 v35, v35, v100
	v_mul_f32_e64 v32, v32, v100
	v_mul_f32_e64 v33, v33, v100
	ds_read_b128 v[148:151], v114 offset:22528
	v_fma_f32 v64, v232, v64, v80
	v_fmac_f32_e32 v64, v159, v180
	v_pk_mul_f32 v[62:63], v[62:63], v[100:101] op_sel_hi:[1,0]
	v_pk_mul_f32 v[60:61], v[60:61], v[100:101] op_sel_hi:[1,0]
	v_mfma_f32_32x32x16_bf16 v[16:31], v[196:199], v[96:99], v[16:31]
	v_mul_f32_e64 v58, v58, v100
	v_mul_f32_e64 v59, v59, v100
	v_mul_f32_e64 v56, v56, v100
	v_mul_f32_e64 v57, v57, v100
	v_mul_f32_e64 v54, v54, v100
	v_mul_f32_e64 v55, v55, v100
	v_pk_mul_f32 v[52:53], v[52:53], v[100:101] op_sel_hi:[1,0]
	v_pk_mul_f32 v[50:51], v[50:51], v[100:101] op_sel_hi:[1,0]
	v_pk_mul_f32 v[48:49], v[48:49], v[100:101] op_sel_hi:[1,0]
	s_waitcnt lgkmcnt(0)
	v_mfma_f32_32x32x16_bf16 v[32:47], v[140:143], v[108:111], v[32:47]
	ds_read_b128 v[196:199], v104 offset:20480
	ds_read_b128 v[140:143], v104 offset:22528
	ds_read_u16 v104, v195 offset:40960
	ds_read_u16 v106, v195 offset:41024
	ds_read_u16 v112, v195 offset:41088
	ds_read_u16 v114, v195 offset:41152
	ds_read_u16 v116, v195 offset:41472
	ds_read_u16 v118, v195 offset:41536
	ds_read_u16 v120, v195 offset:41600
	ds_read_u16 v122, v195 offset:41664
	s_waitcnt lgkmcnt(0)
	v_lshlrev_b32_e32 v104, 16, v104
	v_mul_f32_e32 v124, 0xbfb8aa3b, v104
	v_exp_f32_e32 v124, v124
	s_nop 0
	v_add_f32_e32 v124, 1.0, v124
	v_rcp_f32_e32 v124, v124
	v_mfma_f32_32x32x16_bf16 v[48:63], v[148:151], v[108:111], v[48:63]
	v_mul_f32_e32 v80, v124, v104
	v_lshlrev_b32_e32 v104, 16, v106
	v_mul_f32_e32 v106, 0xbfb8aa3b, v104
	v_exp_f32_e32 v106, v106
	v_mul_f32_e32 v64, v64, v80
	v_cvt_pk_bf16_f32 v64, v64, s0
	v_add_f32_e32 v106, 1.0, v106
	ds_write_b16 v195, v64 offset:40960
	v_fma_f32 v64, v233, v65, v81
	v_lshlrev_b32_e32 v80, 16, v112
	v_rcp_f32_e32 v106, v106
	v_mul_f32_e32 v81, 0xbfb8aa3b, v80
	v_exp_f32_e32 v81, v81
	v_fmac_f32_e32 v64, v159, v181
	v_mul_f32_e32 v65, v106, v104
	v_mul_f32_e32 v64, v64, v65
	v_add_f32_e32 v81, 1.0, v81
	v_rcp_f32_e32 v81, v81
	v_cvt_pk_bf16_f32 v64, v64, s0
	ds_write_b16 v195, v64 offset:41024
	v_fma_f32 v64, v234, v66, v82
	v_lshlrev_b32_e32 v66, 16, v114
	v_mul_f32_e32 v65, v81, v80
	v_mul_f32_e32 v80, 0xbfb8aa3b, v66
	v_exp_f32_e32 v80, v80
	v_fmac_f32_e32 v64, v159, v178
	v_mul_f32_e32 v64, v64, v65
	v_add_f32_e32 v80, 1.0, v80
	v_rcp_f32_e32 v80, v80
	v_cvt_pk_bf16_f32 v64, v64, s0
	ds_write_b16 v195, v64 offset:41088
	v_fma_f32 v64, v235, v67, v83
	v_mul_f32_e32 v65, v80, v66
	v_lshlrev_b32_e32 v66, 16, v116
	v_mul_f32_e32 v67, 0xbfb8aa3b, v66
	v_exp_f32_e32 v67, v67
	v_fmac_f32_e32 v64, v159, v179
	v_mul_f32_e32 v64, v64, v65
	v_add_f32_e32 v67, 1.0, v67
	v_rcp_f32_e32 v67, v67
	v_cvt_pk_bf16_f32 v64, v64, s0
	ds_write_b16 v195, v64 offset:41152
	v_fma_f32 v64, v236, v68, v84
	v_mul_f32_e32 v65, v67, v66
	v_lshlrev_b32_e32 v66, 16, v118
	v_mul_f32_e32 v67, 0xbfb8aa3b, v66
	v_exp_f32_e32 v67, v67
	v_fmac_f32_e32 v64, v159, v176
	v_mul_f32_e32 v64, v64, v65
	v_add_f32_e32 v67, 1.0, v67
	v_rcp_f32_e32 v67, v67
	v_cvt_pk_bf16_f32 v64, v64, s0
	ds_write_b16 v195, v64 offset:41472
	v_fma_f32 v64, v237, v69, v85
	v_mul_f32_e32 v65, v67, v66
	v_lshlrev_b32_e32 v66, 16, v120
	v_mul_f32_e32 v67, 0xbfb8aa3b, v66
	v_exp_f32_e32 v67, v67
	v_fmac_f32_e32 v64, v159, v177
	v_mul_f32_e32 v64, v64, v65
	v_add_f32_e32 v67, 1.0, v67
	v_rcp_f32_e32 v67, v67
	v_cvt_pk_bf16_f32 v64, v64, s0
	ds_write_b16 v195, v64 offset:41536
	v_fma_f32 v64, v238, v70, v86
	v_mul_f32_e32 v65, v67, v66
	v_lshlrev_b32_e32 v66, 16, v122
	v_mul_f32_e32 v67, 0xbfb8aa3b, v66
	v_exp_f32_e32 v67, v67
	v_fmac_f32_e32 v64, v159, v174
	v_mul_f32_e32 v64, v64, v65
	v_add_f32_e32 v67, 1.0, v67
	v_rcp_f32_e32 v67, v67
	v_cvt_pk_bf16_f32 v64, v64, s0
	ds_write_b16 v195, v64 offset:41600
	v_fma_f32 v64, v239, v71, v87
	v_mul_f32_e32 v65, v67, v66
	ds_read_u16 v66, v195 offset:41984
	ds_read_u16 v67, v195 offset:42048
	ds_read_u16 v68, v195 offset:42112
	ds_read_u16 v69, v195 offset:42176
	ds_read_u16 v70, v195 offset:42496
	ds_read_u16 v71, v195 offset:42560
	ds_read_u16 v80, v195 offset:42624
	ds_read_u16 v81, v195 offset:42688
	s_waitcnt lgkmcnt(0)
	v_lshlrev_b32_e32 v66, 16, v66
	v_mul_f32_e32 v82, 0xbfb8aa3b, v66
	v_exp_f32_e32 v82, v82
	v_fmac_f32_e32 v64, v159, v175
	v_mul_f32_e32 v64, v64, v65
	v_add_f32_e32 v82, 1.0, v82
	v_rcp_f32_e32 v82, v82
	v_cvt_pk_bf16_f32 v64, v64, s0
	ds_write_b16 v195, v64 offset:41664
	v_fma_f32 v64, v240, v72, v88
	v_mul_f32_e32 v65, v82, v66
	v_lshlrev_b32_e32 v66, 16, v67
	v_mul_f32_e32 v67, 0xbfb8aa3b, v66
	v_exp_f32_e32 v67, v67
	v_fmac_f32_e32 v64, v159, v172
	v_mul_f32_e32 v64, v64, v65
	v_add_f32_e32 v67, 1.0, v67
	v_rcp_f32_e32 v67, v67
	v_cvt_pk_bf16_f32 v64, v64, s0
	ds_write_b16 v195, v64 offset:41984
	v_fma_f32 v64, v241, v73, v89
	v_mul_f32_e32 v65, v67, v66
	v_lshlrev_b32_e32 v66, 16, v68
	v_mul_f32_e32 v67, 0xbfb8aa3b, v66
	v_exp_f32_e32 v67, v67
	v_fmac_f32_e32 v64, v159, v173
	v_mul_f32_e32 v64, v64, v65
	v_add_f32_e32 v67, 1.0, v67
	v_rcp_f32_e32 v67, v67
	v_cvt_pk_bf16_f32 v64, v64, s0
	ds_write_b16 v195, v64 offset:42048
	v_fma_f32 v64, v242, v74, v90
	v_mul_f32_e32 v65, v67, v66
	v_lshlrev_b32_e32 v66, 16, v69
	v_mul_f32_e32 v67, 0xbfb8aa3b, v66
	v_exp_f32_e32 v67, v67
	v_fmac_f32_e32 v64, v159, v170
	v_mul_f32_e32 v64, v64, v65
	v_add_f32_e32 v67, 1.0, v67
	v_rcp_f32_e32 v67, v67
	v_cvt_pk_bf16_f32 v64, v64, s0
	ds_write_b16 v195, v64 offset:42112
	v_fma_f32 v64, v243, v75, v91
	v_mul_f32_e32 v65, v67, v66
	v_lshlrev_b32_e32 v66, 16, v70
	v_mul_f32_e32 v67, 0xbfb8aa3b, v66
	v_exp_f32_e32 v67, v67
	v_fmac_f32_e32 v64, v159, v171
	v_mul_f32_e32 v64, v64, v65
	v_add_f32_e32 v67, 1.0, v67
	v_rcp_f32_e32 v67, v67
	v_cvt_pk_bf16_f32 v64, v64, s0
	ds_write_b16 v195, v64 offset:42176
	v_fma_f32 v64, v244, v76, v92
	v_mul_f32_e32 v65, v67, v66
	v_lshlrev_b32_e32 v66, 16, v71
	v_mul_f32_e32 v67, 0xbfb8aa3b, v66
	v_exp_f32_e32 v67, v67
	v_fmac_f32_e32 v64, v159, v168
	v_mul_f32_e32 v64, v64, v65
	v_add_f32_e32 v67, 1.0, v67
	v_rcp_f32_e32 v67, v67
	v_cvt_pk_bf16_f32 v64, v64, s0
	ds_write_b16 v195, v64 offset:42496
	v_fma_f32 v64, v245, v77, v93
	v_mul_f32_e32 v65, v67, v66
	v_lshlrev_b32_e32 v66, 16, v80
	v_mul_f32_e32 v67, 0xbfb8aa3b, v66
	v_exp_f32_e32 v67, v67
	v_fmac_f32_e32 v64, v159, v169
	v_mul_f32_e32 v64, v64, v65
	v_add_f32_e32 v67, 1.0, v67
	v_rcp_f32_e32 v67, v67
	v_cvt_pk_bf16_f32 v64, v64, s0
	ds_write_b16 v195, v64 offset:42560
	v_fma_f32 v64, v246, v78, v94
	v_mul_f32_e32 v65, v67, v66
	v_lshlrev_b32_e32 v66, 16, v81
	v_mul_f32_e32 v67, 0xbfb8aa3b, v66
	v_exp_f32_e32 v67, v67
	v_fmac_f32_e32 v64, v159, v166
	v_mul_f32_e32 v64, v64, v65
	v_add_f32_e32 v67, 1.0, v67
	v_rcp_f32_e32 v67, v67
	v_cvt_pk_bf16_f32 v64, v64, s0
	v_fmac_f32_e32 v95, v247, v79
	ds_write_b16 v195, v64 offset:42624
	v_fmac_f32_e32 v95, v159, v167
	v_mul_f32_e32 v64, v67, v66
	v_mul_f32_e32 v64, v95, v64
	v_cvt_pk_bf16_f32 v64, v64, s0
	ds_write_b16 v195, v64 offset:42688
	s_waitcnt lgkmcnt(0)
	v_add3_u32 v68, s34, v102, v164
	ds_read_b128 v[64:67], v68 offset:40960
	ds_read_b128 v[68:71], v68 offset:40976
	v_mfma_f32_32x32x16_bf16 v[32:47], v[196:199], v[96:99], v[32:47]
	s_waitcnt lgkmcnt(0)
	v_lshlrev_b32_e32 v72, 16, v64
	v_and_b32_e32 v64, 0xffff0000, v64
	v_mul_f32_e32 v64, v64, v64
	v_lshlrev_b32_e32 v73, 16, v65
	v_fmac_f32_e32 v64, v72, v72
	v_and_b32_e32 v65, 0xffff0000, v65
	v_fmac_f32_e32 v64, v73, v73
	v_lshlrev_b32_e32 v74, 16, v66
	v_fmac_f32_e32 v64, v65, v65
	v_and_b32_e32 v66, 0xffff0000, v66
	v_fmac_f32_e32 v64, v74, v74
	v_lshlrev_b32_e32 v75, 16, v67
	v_fmac_f32_e32 v64, v66, v66
	v_and_b32_e32 v67, 0xffff0000, v67
	v_fmac_f32_e32 v64, v75, v75
	v_lshlrev_b32_e32 v76, 16, v68
	v_fmac_f32_e32 v64, v67, v67
	v_and_b32_e32 v68, 0xffff0000, v68
	v_fmac_f32_e32 v64, v76, v76
	v_lshlrev_b32_e32 v77, 16, v69
	v_fmac_f32_e32 v64, v68, v68
	v_and_b32_e32 v69, 0xffff0000, v69
	v_fmac_f32_e32 v64, v77, v77
	v_lshlrev_b32_e32 v78, 16, v70
	v_fmac_f32_e32 v64, v69, v69
	v_and_b32_e32 v70, 0xffff0000, v70
	v_fmac_f32_e32 v64, v78, v78
	v_lshlrev_b32_e32 v79, 16, v71
	v_fmac_f32_e32 v64, v70, v70
	v_mfma_f32_32x32x16_bf16 v[48:63], v[140:143], v[96:99], v[48:63]
	v_and_b32_e32 v71, 0xffff0000, v71
	v_fmac_f32_e32 v64, v79, v79
	v_fmac_f32_e32 v64, v71, v71
	ds_bpermute_b32 v65, v185, v64
	s_and_saveexec_b64 s[6:7], vcc
	s_cbranch_execz .LBB0_567
	s_waitcnt lgkmcnt(0)
	v_add_f32_e32 v66, v64, v65
	v_add_u32_e32 v64, s21, v152
	v_lshl_add_u32 v152, v64, 5, s93
	v_lshl_add_u64 v[64:65], v[152:153], 2, s[18:19]
	global_store_dword v[64:65], v66, off
	s_branch .LBB0_567
